# ctx skinny GEMM items: split-K reduce issues its 16 LDS reads together; wave 0 pre-touches the residual rows its epilogue reads
# speedup vs baseline: 1.0638x; 1.0103x over previous
; #define LAS __attribute__((address_space(3)))
;     template <int A0, int A1> __device__ __forceinline__ void run(const f32x4 (&acc)[2][2][4][2], const Unit& u, int wr, int wc, int fr, int fq) const {
;     ...
;             const int col = u.pn * 256 + bj * 128 + wc * 32 + fq * 8;
;             const f32x4 gv0 = *(const f32x4*)(gate + s * NMOD + col) * gmul, gv1 = *(const f32x4*)(gate + s * NMOD + col + 4) * gmul;
;             f32x4 wv0 = (f32x4){0.f, 0.f, 0.f, 0.f}, wv1 = wv0;
;             if (has_next) { wv0 = *(const f32x4*)(nw + col) * (*(const f32x4*)(nscale + s * NMOD + col) + 1.0f); wv1 = *(const f32x4*)(nw + col + 4) * (*(const f32x4*)(nscale + s * NMOD + col + 4) + 1.0f); }
; template <class Epi, int AI>
; __device__ __forceinline__ void skinny_item(LAS unsigned char* lds, const Gemm g, const Epi& E, const Unit u, int wr, int wc, int wave, int lane) {
;     ...
;     __syncthreads();
;     if (wave == 0) {
; #pragma unroll 1
;         for (int w = 0; w < 7; ++w) {
; #pragma unroll
;             for (int bj = 0; bj < 2; ++bj)
; #pragma unroll
;                 for (int m = 0; m < 4; ++m)
; #pragma unroll
;                     for (int n = 0; n < 2; ++n) acc[AI][bj][m][n] += *(const LAS f32x4*)(lds + ((w * 16 + bj * 8 + m * 2 + n) * 64 + lane) * 16);
;         }
;         E.template run<AI, AI + 1>(acc, u, wr, wc, fr, fq);
.LBB0_1330:
	s_and_b64 vcc, exec, s[4:5]
	s_waitcnt lgkmcnt(0)
	s_barrier
	s_cbranch_vccnz .LBB0_1362
	s_mov_b32 s10, 0
	s_or_b32 vcc_lo, s38, s26
	v_add_u32_e32 v248, vcc_lo, v72
	v_ashrrev_i32_e32 v249, 31, v248
	v_lshlrev_b32_e32 v250, 10, v132
	v_mov_b32_e32 v251, 0
	v_lshl_add_u64 v[248:249], v[250:251], 0, v[248:249]
	v_lshlrev_b64 v[248:249], 2, v[248:249]
	v_lshl_add_u64 v[248:249], s[80:81], 0, v[248:249]
	v_mov_b32_e32 v250, 0x10000
	global_load_dword v253, v[248:249], off
	global_load_dword v253, v[248:249], off offset:512
	v_lshl_add_u64 v[248:249], v[248:249], 0, v[250:251]
	global_load_dword v253, v[248:249], off
	global_load_dword v253, v[248:249], off offset:512
	v_lshl_add_u64 v[248:249], v[248:249], 0, v[250:251]
	global_load_dword v253, v[248:249], off
	global_load_dword v253, v[248:249], off offset:512
	v_lshl_add_u64 v[248:249], v[248:249], 0, v[250:251]
	global_load_dword v253, v[248:249], off
	global_load_dword v253, v[248:249], off offset:512
.LBB0_1332:
	v_add_u32_e32 v68, s10, v107
	ds_read_b128 v[190:193], v68
	ds_read_b128 v[194:197], v68 offset:1024
	ds_read_b128 v[198:201], v68 offset:2048
	ds_read_b128 v[202:205], v68 offset:3072
	ds_read_b128 v[206:209], v68 offset:4096
	ds_read_b128 v[210:213], v68 offset:5120
	ds_read_b128 v[214:217], v68 offset:6144
	ds_read_b128 v[218:221], v68 offset:7168
	ds_read_b128 v[222:225], v68 offset:8192
	ds_read_b128 v[226:229], v68 offset:9216
	ds_read_b128 v[230:233], v68 offset:10240
	ds_read_b128 v[234:237], v68 offset:11264
	ds_read_b128 v[240:243], v68 offset:12288
	ds_read_b128 v[244:247], v68 offset:13312
	ds_read_b128 v[248:251], v68 offset:14336
	ds_read_b128 v[64:67], v68 offset:15360
	s_waitcnt lgkmcnt(0)
	v_pk_add_f32 v[58:59], v[58:59], v[192:193]
	v_pk_add_f32 v[56:57], v[56:57], v[190:191]
	v_pk_add_f32 v[62:63], v[62:63], v[196:197]
	v_pk_add_f32 v[60:61], v[60:61], v[194:195]
	v_pk_add_f32 v[54:55], v[54:55], v[200:201]
	v_pk_add_f32 v[52:53], v[52:53], v[198:199]
	v_pk_add_f32 v[50:51], v[50:51], v[204:205]
	v_pk_add_f32 v[48:49], v[48:49], v[202:203]
	v_pk_add_f32 v[46:47], v[46:47], v[208:209]
	v_pk_add_f32 v[44:45], v[44:45], v[206:207]
	v_pk_add_f32 v[42:43], v[42:43], v[212:213]
	v_pk_add_f32 v[40:41], v[40:41], v[210:211]
	v_pk_add_f32 v[38:39], v[38:39], v[216:217]
	v_pk_add_f32 v[36:37], v[36:37], v[214:215]
	v_pk_add_f32 v[34:35], v[34:35], v[220:221]
	v_pk_add_f32 v[32:33], v[32:33], v[218:219]
	v_pk_add_f32 v[30:31], v[30:31], v[224:225]
	v_pk_add_f32 v[28:29], v[28:29], v[222:223]
	v_pk_add_f32 v[26:27], v[26:27], v[228:229]
	v_pk_add_f32 v[24:25], v[24:25], v[226:227]
	v_pk_add_f32 v[18:19], v[18:19], v[232:233]
	v_pk_add_f32 v[16:17], v[16:17], v[230:231]
	v_pk_add_f32 v[22:23], v[22:23], v[236:237]
	v_pk_add_f32 v[20:21], v[20:21], v[234:235]
	v_pk_add_f32 v[6:7], v[6:7], v[242:243]
	v_pk_add_f32 v[4:5], v[4:5], v[240:241]
	v_pk_add_f32 v[10:11], v[10:11], v[246:247]
	v_pk_add_f32 v[8:9], v[8:9], v[244:245]
	v_pk_add_f32 v[2:3], v[2:3], v[250:251]
	v_pk_add_f32 v[0:1], v[0:1], v[248:249]
	v_pk_add_f32 v[14:15], v[14:15], v[66:67]
	v_pk_add_f32 v[12:13], v[12:13], v[64:65]
	s_addk_i32 s10, 0x4000
	s_cmp_lg_u32 s10, 0x1c000
	s_cbranch_scc1 .LBB0_1332
	s_or_b32 s10, s38, s26
	v_add_u32_e32 v84, s10, v72
	v_ashrrev_i32_e32 v85, 31, v84
	v_lshl_add_u64 v[68:69], v[84:85], 2, s[84:85]
	global_load_dwordx4 v[64:67], v[68:69], off offset:16
	s_nop 0
	global_load_dwordx4 v[68:71], v[68:69], off
	v_mov_b32_e32 v92, 0
	v_cndmask_b32_e64 v86, 0, 1, s[74:75]
	v_cmp_ne_u32_e64 s[10:11], 1, v86
	s_andn2_b64 vcc, exec, s[74:75]
	v_mov_b32_e32 v93, v92
	v_mov_b32_e32 v94, v92
	v_mov_b32_e32 v95, v92
	v_mov_b32_e32 v96, v92
	v_mov_b32_e32 v97, v92
	v_mov_b32_e32 v98, v92
	v_mov_b32_e32 v99, v92
	s_cbranch_vccnz .LBB0_1335
	v_lshlrev_b64 v[94:95], 2, v[84:85]
	v_lshl_add_u64 v[90:91], s[86:87], 0, v[94:95]
	global_load_dwordx4 v[86:89], v[90:91], off
	s_nop 0
	global_load_dwordx4 v[90:93], v[90:91], off offset:16
	v_lshl_add_u64 v[98:99], s[16:17], 0, v[94:95]
	global_load_dwordx4 v[94:97], v[98:99], off
	global_load_dwordx4 v[100:103], v[98:99], off offset:16
	s_waitcnt vmcnt(3)
	v_pk_add_f32 v[88:89], v[88:89], 1.0 op_sel_hi:[1,0]
	v_pk_add_f32 v[86:87], v[86:87], 1.0 op_sel_hi:[1,0]
	s_waitcnt vmcnt(2)
	v_pk_add_f32 v[92:93], v[92:93], 1.0 op_sel_hi:[1,0]
	v_pk_add_f32 v[90:91], v[90:91], 1.0 op_sel_hi:[1,0]
	s_waitcnt vmcnt(1)
	v_pk_mul_f32 v[98:99], v[96:97], v[88:89]
	v_pk_mul_f32 v[96:97], v[94:95], v[86:87]
	s_waitcnt vmcnt(0)
	v_pk_mul_f32 v[94:95], v[102:103], v[92:93]
	v_pk_mul_f32 v[92:93], v[100:101], v[90:91]

; #define LAS __attribute__((address_space(3)))
;     template <int A0, int A1> __device__ __forceinline__ void run(const f32x4 (&acc)[2][2][4][2], const Unit& u, int wr, int wc, int fr, int fq) const {
;     ...
;             const int col = u.pn * 256 + bj * 128 + wc * 32 + fq * 8;
;             const f32x4 gv0 = *(const f32x4*)(gate + s * NMOD + col) * gmul, gv1 = *(const f32x4*)(gate + s * NMOD + col + 4) * gmul;
;             f32x4 wv0 = (f32x4){0.f, 0.f, 0.f, 0.f}, wv1 = wv0;
;             if (has_next) { wv0 = *(const f32x4*)(nw + col) * (*(const f32x4*)(nscale + s * NMOD + col) + 1.0f); wv1 = *(const f32x4*)(nw + col + 4) * (*(const f32x4*)(nscale + s * NMOD + col + 4) + 1.0f); }
; template <class Epi, int AI>
; __device__ __forceinline__ void skinny_item(LAS unsigned char* lds, const Gemm g, const Epi& E, const Unit u, int wr, int wc, int wave, int lane) {
;     ...
;     __syncthreads();
;     if (wave == 0) {
; #pragma unroll 1
;         for (int w = 0; w < 7; ++w) {
; #pragma unroll
;             for (int bj = 0; bj < 2; ++bj)
; #pragma unroll
;                 for (int m = 0; m < 4; ++m)
; #pragma unroll
;                     for (int n = 0; n < 2; ++n) acc[AI][bj][m][n] += *(const LAS f32x4*)(lds + ((w * 16 + bj * 8 + m * 2 + n) * 64 + lane) * 16);
;         }
;         E.template run<AI, AI + 1>(acc, u, wr, wc, fr, fq);
.LBB0_1370:
	s_and_b64 vcc, exec, s[4:5]
	s_waitcnt lgkmcnt(0)
	s_barrier
	s_cbranch_vccnz .LBB0_1321
	s_mov_b32 s8, 0
	s_or_b32 vcc_lo, s38, s26
	v_add_u32_e32 v248, vcc_lo, v72
	v_ashrrev_i32_e32 v249, 31, v248
	v_lshlrev_b32_e32 v250, 10, v132
	v_mov_b32_e32 v251, 0
	v_lshl_add_u64 v[248:249], v[250:251], 0, v[248:249]
	v_lshlrev_b64 v[248:249], 2, v[248:249]
	v_lshl_add_u64 v[248:249], s[80:81], 0, v[248:249]
	v_mov_b32_e32 v250, 0x10000
	global_load_dword v253, v[248:249], off
	global_load_dword v253, v[248:249], off offset:512
	v_lshl_add_u64 v[248:249], v[248:249], 0, v[250:251]
	global_load_dword v253, v[248:249], off
	global_load_dword v253, v[248:249], off offset:512
	v_lshl_add_u64 v[248:249], v[248:249], 0, v[250:251]
	global_load_dword v253, v[248:249], off
	global_load_dword v253, v[248:249], off offset:512
	v_lshl_add_u64 v[248:249], v[248:249], 0, v[250:251]
	global_load_dword v253, v[248:249], off
	global_load_dword v253, v[248:249], off offset:512
.LBB0_1372:
	v_add_u32_e32 v68, s8, v107
	ds_read_b128 v[190:193], v68
	ds_read_b128 v[194:197], v68 offset:1024
	ds_read_b128 v[198:201], v68 offset:2048
	ds_read_b128 v[202:205], v68 offset:3072
	ds_read_b128 v[206:209], v68 offset:4096
	ds_read_b128 v[210:213], v68 offset:5120
	ds_read_b128 v[214:217], v68 offset:6144
	ds_read_b128 v[218:221], v68 offset:7168
	ds_read_b128 v[222:225], v68 offset:8192
	ds_read_b128 v[226:229], v68 offset:9216
	ds_read_b128 v[230:233], v68 offset:10240
	ds_read_b128 v[234:237], v68 offset:11264
	ds_read_b128 v[240:243], v68 offset:12288
	ds_read_b128 v[244:247], v68 offset:13312
	ds_read_b128 v[248:251], v68 offset:14336
	ds_read_b128 v[64:67], v68 offset:15360
	s_waitcnt lgkmcnt(0)
	v_pk_add_f32 v[58:59], v[58:59], v[192:193]
	v_pk_add_f32 v[56:57], v[56:57], v[190:191]
	v_pk_add_f32 v[62:63], v[62:63], v[196:197]
	v_pk_add_f32 v[60:61], v[60:61], v[194:195]
	v_pk_add_f32 v[54:55], v[54:55], v[200:201]
	v_pk_add_f32 v[52:53], v[52:53], v[198:199]
	v_pk_add_f32 v[50:51], v[50:51], v[204:205]
	v_pk_add_f32 v[48:49], v[48:49], v[202:203]
	v_pk_add_f32 v[46:47], v[46:47], v[208:209]
	v_pk_add_f32 v[44:45], v[44:45], v[206:207]
	v_pk_add_f32 v[42:43], v[42:43], v[212:213]
	v_pk_add_f32 v[40:41], v[40:41], v[210:211]
	v_pk_add_f32 v[38:39], v[38:39], v[216:217]
	v_pk_add_f32 v[36:37], v[36:37], v[214:215]
	v_pk_add_f32 v[34:35], v[34:35], v[220:221]
	v_pk_add_f32 v[32:33], v[32:33], v[218:219]
	v_pk_add_f32 v[30:31], v[30:31], v[224:225]
	v_pk_add_f32 v[28:29], v[28:29], v[222:223]
	v_pk_add_f32 v[26:27], v[26:27], v[228:229]
	v_pk_add_f32 v[24:25], v[24:25], v[226:227]
	v_pk_add_f32 v[18:19], v[18:19], v[232:233]
	v_pk_add_f32 v[16:17], v[16:17], v[230:231]
	v_pk_add_f32 v[22:23], v[22:23], v[236:237]
	v_pk_add_f32 v[20:21], v[20:21], v[234:235]
	v_pk_add_f32 v[6:7], v[6:7], v[242:243]
	v_pk_add_f32 v[4:5], v[4:5], v[240:241]
	v_pk_add_f32 v[10:11], v[10:11], v[246:247]
	v_pk_add_f32 v[8:9], v[8:9], v[244:245]
	v_pk_add_f32 v[2:3], v[2:3], v[250:251]
	v_pk_add_f32 v[0:1], v[0:1], v[248:249]
	v_pk_add_f32 v[14:15], v[14:15], v[66:67]
	v_pk_add_f32 v[12:13], v[12:13], v[64:65]
	s_addk_i32 s8, 0x4000
	s_cmp_lg_u32 s8, 0x1c000
	s_cbranch_scc1 .LBB0_1372
	s_or_b32 s8, s38, s26
	v_add_u32_e32 v84, s8, v72
	v_ashrrev_i32_e32 v85, 31, v84
	v_lshl_add_u64 v[68:69], v[84:85], 2, s[84:85]
	global_load_dwordx4 v[64:67], v[68:69], off offset:16
	s_nop 0
	global_load_dwordx4 v[68:71], v[68:69], off
	v_mov_b32_e32 v92, 0
	v_cndmask_b32_e64 v86, 0, 1, s[74:75]
	v_cmp_ne_u32_e64 s[8:9], 1, v86
	s_andn2_b64 vcc, exec, s[74:75]
	v_mov_b32_e32 v93, v92
	v_mov_b32_e32 v94, v92
	v_mov_b32_e32 v95, v92
	v_mov_b32_e32 v96, v92
	v_mov_b32_e32 v97, v92
	v_mov_b32_e32 v98, v92
	v_mov_b32_e32 v99, v92
	s_cbranch_vccnz .LBB0_1375
	v_lshlrev_b64 v[94:95], 2, v[84:85]
	v_lshl_add_u64 v[90:91], s[86:87], 0, v[94:95]
	global_load_dwordx4 v[86:89], v[90:91], off
	s_nop 0
	global_load_dwordx4 v[90:93], v[90:91], off offset:16
	v_lshl_add_u64 v[98:99], s[16:17], 0, v[94:95]
	global_load_dwordx4 v[94:97], v[98:99], off
	global_load_dwordx4 v[100:103], v[98:99], off offset:16
	s_waitcnt vmcnt(3)
	v_pk_add_f32 v[88:89], v[88:89], 1.0 op_sel_hi:[1,0]
	v_pk_add_f32 v[86:87], v[86:87], 1.0 op_sel_hi:[1,0]
	s_waitcnt vmcnt(2)
	v_pk_add_f32 v[92:93], v[92:93], 1.0 op_sel_hi:[1,0]
	v_pk_add_f32 v[90:91], v[90:91], 1.0 op_sel_hi:[1,0]
	s_waitcnt vmcnt(1)
	v_pk_mul_f32 v[98:99], v[96:97], v[88:89]
	v_pk_mul_f32 v[96:97], v[94:95], v[86:87]
	s_waitcnt vmcnt(0)
	v_pk_mul_f32 v[94:95], v[102:103], v[92:93]
	v_pk_mul_f32 v[92:93], v[100:101], v[90:91]
